# P7 residual epilogue hand-scheduled like P4's (4 row groups in flight), on top of v69
# speedup vs baseline: 1.0116x; 1.0116x over previous
; #define EPI_FENCE() asm volatile("" ::: "memory")
; __device__ __forceinline__ u32x4 pack8(f32x4 a, f32x4 b) { u32x4 w; w.x = cvt_pk_bf16(a[0], a[1]); w.y = cvt_pk_bf16(a[2], a[3]); w.z = cvt_pk_bf16(b[0], b[1]); w.w = cvt_pk_bf16(b[2], b[3]); return w; }
; __device__ __forceinline__ float dot4(f32x4 a) { return (a[0] * a[0] + a[1] * a[1]) + (a[2] * a[2] + a[3] * a[3]); }
;   __device__ __forceinline__ void operator()(const AccT& acc, const pg8::Unit& u, int wr, int wc, int fr, int fq) const {
;     const int row0 = u.pm * 256 + wr * 64 + fr, col0 = u.pn * 256 + wc * 32 + 8 * fq;
; #pragma unroll
;     for (int ai = 0; ai < 2; ++ai)
; #pragma unroll
;       for (int m = 0; m < 4; ++m) { const int row = row0 + ai * 128 + m * 16; const size_t off = (size_t)row * DM + col0; float s = 0.f;
; #pragma unroll
;         for (int bj = 0; bj < 2; ++bj) { const int co = bj * 128;
;           const f32x4 v0 = *(const f32x4*)(base + off + co) + acc[ai][bj][m][0], v1 = *(const f32x4*)(base + off + co + 4) + acc[ai][bj][m][1];
;           *(f32x4*)(X + off + co) = v0; *(f32x4*)(X + off + co + 4) = v1; s += dot4(v0) + dot4(v1);
;           if (xb) { const f32x4 g0 = *(const f32x4*)(g + col0 + co), g1 = *(const f32x4*)(g + col0 + co + 4); *(u32x4*)(xb + off + co) = pack8(v0 * g0, v1 * g1); } }
;         s += __shfl_xor(s, 16); s += __shfl_xor(s, 32);
;         if (fq == 0) unsafeAtomicAdd(ss + row, s);
;         if (m & 1) EPI_FENCE(); }
;   }
.LBB0_789:
	v_lshl_add_u32 v149, s56, 8, v150
	v_lshl_or_b32 v250, s57, 8, v152
	v_lshlrev_b32_e32 v250, 2, v250
	v_lshl_add_u32 v148, v149, 13, v250
	v_lshlrev_b32_e32 v149, 2, v149
	global_load_dwordx4 v[144:147], v250, s[26:27]
	global_load_dwordx4 v[158:161], v250, s[26:27] offset:16
	global_load_dwordx4 v[162:165], v250, s[26:27] offset:512
	global_load_dwordx4 v[166:169], v250, s[26:27] offset:528
	v_xor_b32_e32 v186, 16, v156
	v_xor_b32_e32 v252, 32, v156
	v_lshlrev_b32_e32 v186, 2, v186
	v_lshlrev_b32_e32 v252, 2, v252
	global_load_dwordx4 v[170:173], v148, s[72:73]
	global_load_dwordx4 v[174:177], v148, s[72:73] offset:16
	global_load_dwordx4 v[178:181], v148, s[72:73] offset:512
	global_load_dwordx4 v[182:185], v148, s[72:73] offset:528
	v_add_u32_e32 v251, 0x20000, v148
	global_load_dwordx4 v[188:191], v251, s[72:73]
	global_load_dwordx4 v[194:197], v251, s[72:73] offset:16
	global_load_dwordx4 v[198:201], v251, s[72:73] offset:512
	global_load_dwordx4 v[202:205], v251, s[72:73] offset:528
	v_add_u32_e32 v251, 0x40000, v148
	global_load_dwordx4 v[206:209], v251, s[72:73]
	global_load_dwordx4 v[210:213], v251, s[72:73] offset:16
	global_load_dwordx4 v[214:217], v251, s[72:73] offset:512
	global_load_dwordx4 v[218:221], v251, s[72:73] offset:528
	v_add_u32_e32 v251, 0x60000, v148
	global_load_dwordx4 v[232:235], v251, s[72:73]
	global_load_dwordx4 v[236:239], v251, s[72:73] offset:16
	global_load_dwordx4 v[240:243], v251, s[72:73] offset:512
	global_load_dwordx4 v[244:247], v251, s[72:73] offset:528
	s_waitcnt vmcnt(12)
	v_pk_add_f32 v[120:121], v[120:121], v[170:171]
	v_pk_add_f32 v[122:123], v[122:123], v[172:173]
	v_pk_add_f32 v[124:125], v[124:125], v[174:175]
	v_pk_add_f32 v[126:127], v[126:127], v[176:177]
	v_pk_add_f32 v[116:117], v[116:117], v[178:179]
	v_pk_add_f32 v[118:119], v[118:119], v[180:181]
	v_pk_add_f32 v[112:113], v[112:113], v[182:183]
	v_pk_add_f32 v[114:115], v[114:115], v[184:185]
	global_store_dwordx4 v148, v[120:123], s[72:73]
	global_store_dwordx4 v148, v[124:127], s[72:73] offset:16
	global_store_dwordx4 v148, v[116:119], s[72:73] offset:512
	global_store_dwordx4 v148, v[112:115], s[72:73] offset:528
	v_mul_f32_e32 v248, v120, v120
	v_mul_f32_e32 v249, v121, v121
	v_fmac_f32_e32 v248, v122, v122
	v_fmac_f32_e32 v249, v123, v123
	v_fmac_f32_e32 v248, v124, v124
	v_fmac_f32_e32 v249, v125, v125
	v_fmac_f32_e32 v248, v126, v126
	v_fmac_f32_e32 v249, v127, v127
	v_fmac_f32_e32 v248, v116, v116
	v_fmac_f32_e32 v249, v117, v117
	v_fmac_f32_e32 v248, v118, v118
	v_fmac_f32_e32 v249, v119, v119
	v_fmac_f32_e32 v248, v112, v112
	v_fmac_f32_e32 v249, v113, v113
	v_fmac_f32_e32 v248, v114, v114
	v_fmac_f32_e32 v249, v115, v115
	v_add_f32_e32 v248, v248, v249
	ds_bpermute_b32 v249, v186, v248
	v_pk_mul_f32 v[170:171], v[120:121], v[144:145]
	v_pk_mul_f32 v[172:173], v[122:123], v[146:147]
	v_pk_mul_f32 v[174:175], v[124:125], v[158:159]
	v_pk_mul_f32 v[176:177], v[126:127], v[160:161]
	v_pk_mul_f32 v[178:179], v[116:117], v[162:163]
	v_pk_mul_f32 v[180:181], v[118:119], v[164:165]
	v_pk_mul_f32 v[182:183], v[112:113], v[166:167]
	v_pk_mul_f32 v[184:185], v[114:115], v[168:169]
	v_cvt_pk_bf16_f32 v170, v170, v171
	v_cvt_pk_bf16_f32 v171, v172, v173
	v_cvt_pk_bf16_f32 v172, v174, v175
	v_cvt_pk_bf16_f32 v173, v176, v177
	v_cvt_pk_bf16_f32 v178, v178, v179
	v_cvt_pk_bf16_f32 v179, v180, v181
	v_cvt_pk_bf16_f32 v180, v182, v183
	v_cvt_pk_bf16_f32 v181, v184, v185
	v_lshrrev_b32_e32 v250, 1, v148
	global_store_dwordx4 v250, v[170:173], s[16:17]
	global_store_dwordx4 v250, v[178:181], s[16:17] offset:256
	s_waitcnt lgkmcnt(0)
	v_add_f32_e32 v248, v248, v249
	ds_bpermute_b32 v249, v252, v248
	s_nop 0
	v_add_u32_e32 v251, 0x100000, v148
	global_load_dwordx4 v[170:173], v251, s[72:73]
	global_load_dwordx4 v[174:177], v251, s[72:73] offset:16
	global_load_dwordx4 v[178:181], v251, s[72:73] offset:512
	global_load_dwordx4 v[182:185], v251, s[72:73] offset:528
	s_waitcnt lgkmcnt(0)
	v_add_f32_e32 v248, v248, v249
	s_and_saveexec_b64 s[24:25], s[2:3]
	global_atomic_add_f32 v149, v248, s[18:19]
	s_mov_b64 exec, s[24:25]
	s_waitcnt vmcnt(19)
	v_pk_add_f32 v[108:109], v[108:109], v[188:189]
	v_pk_add_f32 v[110:111], v[110:111], v[190:191]
	v_pk_add_f32 v[104:105], v[104:105], v[194:195]
	v_pk_add_f32 v[106:107], v[106:107], v[196:197]
	v_pk_add_f32 v[100:101], v[100:101], v[198:199]
	v_pk_add_f32 v[102:103], v[102:103], v[200:201]
	v_pk_add_f32 v[96:97], v[96:97], v[202:203]
	v_pk_add_f32 v[98:99], v[98:99], v[204:205]
	v_add_u32_e32 v251, 0x20000, v148
	global_store_dwordx4 v251, v[108:111], s[72:73]
	global_store_dwordx4 v251, v[104:107], s[72:73] offset:16
	global_store_dwordx4 v251, v[100:103], s[72:73] offset:512
	global_store_dwordx4 v251, v[96:99], s[72:73] offset:528
	v_mul_f32_e32 v248, v108, v108
	v_mul_f32_e32 v249, v109, v109
	v_fmac_f32_e32 v248, v110, v110
	v_fmac_f32_e32 v249, v111, v111
	v_fmac_f32_e32 v248, v104, v104
	v_fmac_f32_e32 v249, v105, v105
	v_fmac_f32_e32 v248, v106, v106
	v_fmac_f32_e32 v249, v107, v107
	v_fmac_f32_e32 v248, v100, v100
	v_fmac_f32_e32 v249, v101, v101
	v_fmac_f32_e32 v248, v102, v102
	v_fmac_f32_e32 v249, v103, v103
	v_fmac_f32_e32 v248, v96, v96
	v_fmac_f32_e32 v249, v97, v97
	v_fmac_f32_e32 v248, v98, v98
	v_fmac_f32_e32 v249, v99, v99
	v_add_f32_e32 v248, v248, v249
	ds_bpermute_b32 v249, v186, v248
	v_pk_mul_f32 v[188:189], v[108:109], v[144:145]
	v_pk_mul_f32 v[190:191], v[110:111], v[146:147]
	v_pk_mul_f32 v[194:195], v[104:105], v[158:159]
	v_pk_mul_f32 v[196:197], v[106:107], v[160:161]
	v_pk_mul_f32 v[198:199], v[100:101], v[162:163]
	v_pk_mul_f32 v[200:201], v[102:103], v[164:165]
	v_pk_mul_f32 v[202:203], v[96:97], v[166:167]
	v_pk_mul_f32 v[204:205], v[98:99], v[168:169]
	v_cvt_pk_bf16_f32 v188, v188, v189
	v_cvt_pk_bf16_f32 v189, v190, v191
	v_cvt_pk_bf16_f32 v190, v194, v195
	v_cvt_pk_bf16_f32 v191, v196, v197
	v_cvt_pk_bf16_f32 v198, v198, v199
	v_cvt_pk_bf16_f32 v199, v200, v201
	v_cvt_pk_bf16_f32 v200, v202, v203
	v_cvt_pk_bf16_f32 v201, v204, v205
	v_lshrrev_b32_e32 v250, 1, v251
	global_store_dwordx4 v250, v[188:191], s[16:17]
	global_store_dwordx4 v250, v[198:201], s[16:17] offset:256
	s_waitcnt lgkmcnt(0)
; #define EPI_FENCE() asm volatile("" ::: "memory")
; __device__ __forceinline__ u32x4 pack8(f32x4 a, f32x4 b) { u32x4 w; w.x = cvt_pk_bf16(a[0], a[1]); w.y = cvt_pk_bf16(a[2], a[3]); w.z = cvt_pk_bf16(b[0], b[1]); w.w = cvt_pk_bf16(b[2], b[3]); return w; }
; __device__ __forceinline__ float dot4(f32x4 a) { return (a[0] * a[0] + a[1] * a[1]) + (a[2] * a[2] + a[3] * a[3]); }
;   __device__ __forceinline__ void operator()(const AccT& acc, const pg8::Unit& u, int wr, int wc, int fr, int fq) const {
;     const int row0 = u.pm * 256 + wr * 64 + fr, col0 = u.pn * 256 + wc * 32 + 8 * fq;
; #pragma unroll
;     for (int ai = 0; ai < 2; ++ai)
; #pragma unroll
;       for (int m = 0; m < 4; ++m) { const int row = row0 + ai * 128 + m * 16; const size_t off = (size_t)row * DM + col0; float s = 0.f;
; #pragma unroll
;         for (int bj = 0; bj < 2; ++bj) { const int co = bj * 128;
;           const f32x4 v0 = *(const f32x4*)(base + off + co) + acc[ai][bj][m][0], v1 = *(const f32x4*)(base + off + co + 4) + acc[ai][bj][m][1];
;           *(f32x4*)(X + off + co) = v0; *(f32x4*)(X + off + co + 4) = v1; s += dot4(v0) + dot4(v1);
;           if (xb) { const f32x4 g0 = *(const f32x4*)(g + col0 + co), g1 = *(const f32x4*)(g + col0 + co + 4); *(u32x4*)(xb + off + co) = pack8(v0 * g0, v1 * g1); } }
;         s += __shfl_xor(s, 16); s += __shfl_xor(s, 32);
;         if (fq == 0) unsafeAtomicAdd(ss + row, s);
;         if (m & 1) EPI_FENCE(); }
;   }
	v_add_f32_e32 v248, v248, v249
	ds_bpermute_b32 v249, v252, v248
	v_add_u32_e32 v250, 0x40, v149
	s_nop 0
	v_add_u32_e32 v251, 0x120000, v148
	global_load_dwordx4 v[188:191], v251, s[72:73]
	global_load_dwordx4 v[194:197], v251, s[72:73] offset:16
	global_load_dwordx4 v[198:201], v251, s[72:73] offset:512
	global_load_dwordx4 v[202:205], v251, s[72:73] offset:528
	s_waitcnt lgkmcnt(0)
	v_add_f32_e32 v248, v248, v249
	s_and_saveexec_b64 s[24:25], s[2:3]
	global_atomic_add_f32 v250, v248, s[18:19]
	s_mov_b64 exec, s[24:25]
	s_waitcnt vmcnt(26)
	v_pk_add_f32 v[92:93], v[92:93], v[206:207]
	v_pk_add_f32 v[94:95], v[94:95], v[208:209]
	v_pk_add_f32 v[88:89], v[88:89], v[210:211]
	v_pk_add_f32 v[90:91], v[90:91], v[212:213]
	v_pk_add_f32 v[84:85], v[84:85], v[214:215]
	v_pk_add_f32 v[86:87], v[86:87], v[216:217]
	v_pk_add_f32 v[80:81], v[80:81], v[218:219]
	v_pk_add_f32 v[82:83], v[82:83], v[220:221]
	v_add_u32_e32 v251, 0x40000, v148
	global_store_dwordx4 v251, v[92:95], s[72:73]
	global_store_dwordx4 v251, v[88:91], s[72:73] offset:16
	global_store_dwordx4 v251, v[84:87], s[72:73] offset:512
	global_store_dwordx4 v251, v[80:83], s[72:73] offset:528
	v_mul_f32_e32 v248, v92, v92
	v_mul_f32_e32 v249, v93, v93
	v_fmac_f32_e32 v248, v94, v94
	v_fmac_f32_e32 v249, v95, v95
	v_fmac_f32_e32 v248, v88, v88
	v_fmac_f32_e32 v249, v89, v89
	v_fmac_f32_e32 v248, v90, v90
	v_fmac_f32_e32 v249, v91, v91
	v_fmac_f32_e32 v248, v84, v84
	v_fmac_f32_e32 v249, v85, v85
	v_fmac_f32_e32 v248, v86, v86
	v_fmac_f32_e32 v249, v87, v87
	v_fmac_f32_e32 v248, v80, v80
	v_fmac_f32_e32 v249, v81, v81
	v_fmac_f32_e32 v248, v82, v82
	v_fmac_f32_e32 v249, v83, v83
	v_add_f32_e32 v248, v248, v249
	ds_bpermute_b32 v249, v186, v248
	v_pk_mul_f32 v[206:207], v[92:93], v[144:145]
	v_pk_mul_f32 v[208:209], v[94:95], v[146:147]
	v_pk_mul_f32 v[210:211], v[88:89], v[158:159]
	v_pk_mul_f32 v[212:213], v[90:91], v[160:161]
	v_pk_mul_f32 v[214:215], v[84:85], v[162:163]
	v_pk_mul_f32 v[216:217], v[86:87], v[164:165]
	v_pk_mul_f32 v[218:219], v[80:81], v[166:167]
	v_pk_mul_f32 v[220:221], v[82:83], v[168:169]
	v_cvt_pk_bf16_f32 v206, v206, v207
	v_cvt_pk_bf16_f32 v207, v208, v209
	v_cvt_pk_bf16_f32 v208, v210, v211
	v_cvt_pk_bf16_f32 v209, v212, v213
	v_cvt_pk_bf16_f32 v214, v214, v215
	v_cvt_pk_bf16_f32 v215, v216, v217
	v_cvt_pk_bf16_f32 v216, v218, v219
	v_cvt_pk_bf16_f32 v217, v220, v221
	v_lshrrev_b32_e32 v250, 1, v251
	global_store_dwordx4 v250, v[206:209], s[16:17]
	global_store_dwordx4 v250, v[214:217], s[16:17] offset:256
	s_waitcnt lgkmcnt(0)
	v_add_f32_e32 v248, v248, v249
	ds_bpermute_b32 v249, v252, v248
	v_add_u32_e32 v250, 0x80, v149
	s_nop 0
	v_add_u32_e32 v251, 0x140000, v148
	global_load_dwordx4 v[206:209], v251, s[72:73]
	global_load_dwordx4 v[210:213], v251, s[72:73] offset:16
	global_load_dwordx4 v[214:217], v251, s[72:73] offset:512
	global_load_dwordx4 v[218:221], v251, s[72:73] offset:528
	s_waitcnt lgkmcnt(0)
	v_add_f32_e32 v248, v248, v249
	s_and_saveexec_b64 s[24:25], s[2:3]
	global_atomic_add_f32 v250, v248, s[18:19]
	s_mov_b64 exec, s[24:25]
	s_waitcnt vmcnt(33)
	v_pk_add_f32 v[76:77], v[76:77], v[232:233]
	v_pk_add_f32 v[78:79], v[78:79], v[234:235]
	v_pk_add_f32 v[72:73], v[72:73], v[236:237]
	v_pk_add_f32 v[74:75], v[74:75], v[238:239]
	v_pk_add_f32 v[68:69], v[68:69], v[240:241]
	v_pk_add_f32 v[70:71], v[70:71], v[242:243]
	v_pk_add_f32 v[64:65], v[64:65], v[244:245]
	v_pk_add_f32 v[66:67], v[66:67], v[246:247]
	v_add_u32_e32 v251, 0x60000, v148
	global_store_dwordx4 v251, v[76:79], s[72:73]
	global_store_dwordx4 v251, v[72:75], s[72:73] offset:16
	global_store_dwordx4 v251, v[68:71], s[72:73] offset:512
	global_store_dwordx4 v251, v[64:67], s[72:73] offset:528
	v_mul_f32_e32 v248, v76, v76
	v_mul_f32_e32 v249, v77, v77
	v_fmac_f32_e32 v248, v78, v78
	v_fmac_f32_e32 v249, v79, v79
	v_fmac_f32_e32 v248, v72, v72
	v_fmac_f32_e32 v249, v73, v73
	v_fmac_f32_e32 v248, v74, v74
	v_fmac_f32_e32 v249, v75, v75
	v_fmac_f32_e32 v248, v68, v68
	v_fmac_f32_e32 v249, v69, v69
	v_fmac_f32_e32 v248, v70, v70
	v_fmac_f32_e32 v249, v71, v71
	v_fmac_f32_e32 v248, v64, v64
	v_fmac_f32_e32 v249, v65, v65
	v_fmac_f32_e32 v248, v66, v66
	v_fmac_f32_e32 v249, v67, v67
	v_add_f32_e32 v248, v248, v249
	ds_bpermute_b32 v249, v186, v248
	v_pk_mul_f32 v[232:233], v[76:77], v[144:145]
	v_pk_mul_f32 v[234:235], v[78:79], v[146:147]
	v_pk_mul_f32 v[236:237], v[72:73], v[158:159]
	v_pk_mul_f32 v[238:239], v[74:75], v[160:161]
	v_pk_mul_f32 v[240:241], v[68:69], v[162:163]
	v_pk_mul_f32 v[242:243], v[70:71], v[164:165]
	v_pk_mul_f32 v[244:245], v[64:65], v[166:167]
	v_pk_mul_f32 v[246:247], v[66:67], v[168:169]
	v_cvt_pk_bf16_f32 v232, v232, v233
	v_cvt_pk_bf16_f32 v233, v234, v235
	v_cvt_pk_bf16_f32 v234, v236, v237
	v_cvt_pk_bf16_f32 v235, v238, v239
	v_cvt_pk_bf16_f32 v240, v240, v241
	v_cvt_pk_bf16_f32 v241, v242, v243
	v_cvt_pk_bf16_f32 v242, v244, v245
	v_cvt_pk_bf16_f32 v243, v246, v247
	v_lshrrev_b32_e32 v250, 1, v251
	global_store_dwordx4 v250, v[232:235], s[16:17]
	global_store_dwordx4 v250, v[240:243], s[16:17] offset:256
	s_waitcnt lgkmcnt(0)
	v_add_f32_e32 v248, v248, v249
	ds_bpermute_b32 v249, v252, v248
	v_add_u32_e32 v250, 0xc0, v149
	s_nop 0
	v_add_u32_e32 v251, 0x160000, v148
	global_load_dwordx4 v[232:235], v251, s[72:73]
	global_load_dwordx4 v[236:239], v251, s[72:73] offset:16
	global_load_dwordx4 v[240:243], v251, s[72:73] offset:512
	global_load_dwordx4 v[244:247], v251, s[72:73] offset:528
	s_waitcnt lgkmcnt(0)
	v_add_f32_e32 v248, v248, v249
	s_and_saveexec_b64 s[24:25], s[2:3]
	global_atomic_add_f32 v250, v248, s[18:19]
	s_mov_b64 exec, s[24:25]
	s_waitcnt vmcnt(34)
; #define EPI_FENCE() asm volatile("" ::: "memory")
; __device__ __forceinline__ u32x4 pack8(f32x4 a, f32x4 b) { u32x4 w; w.x = cvt_pk_bf16(a[0], a[1]); w.y = cvt_pk_bf16(a[2], a[3]); w.z = cvt_pk_bf16(b[0], b[1]); w.w = cvt_pk_bf16(b[2], b[3]); return w; }
; __device__ __forceinline__ float dot4(f32x4 a) { return (a[0] * a[0] + a[1] * a[1]) + (a[2] * a[2] + a[3] * a[3]); }
;   __device__ __forceinline__ void operator()(const AccT& acc, const pg8::Unit& u, int wr, int wc, int fr, int fq) const {
;     const int row0 = u.pm * 256 + wr * 64 + fr, col0 = u.pn * 256 + wc * 32 + 8 * fq;
; #pragma unroll
;     for (int ai = 0; ai < 2; ++ai)
; #pragma unroll
;       for (int m = 0; m < 4; ++m) { const int row = row0 + ai * 128 + m * 16; const size_t off = (size_t)row * DM + col0; float s = 0.f;
; #pragma unroll
;         for (int bj = 0; bj < 2; ++bj) { const int co = bj * 128;
;           const f32x4 v0 = *(const f32x4*)(base + off + co) + acc[ai][bj][m][0], v1 = *(const f32x4*)(base + off + co + 4) + acc[ai][bj][m][1];
;           *(f32x4*)(X + off + co) = v0; *(f32x4*)(X + off + co + 4) = v1; s += dot4(v0) + dot4(v1);
;           if (xb) { const f32x4 g0 = *(const f32x4*)(g + col0 + co), g1 = *(const f32x4*)(g + col0 + co + 4); *(u32x4*)(xb + off + co) = pack8(v0 * g0, v1 * g1); } }
;         s += __shfl_xor(s, 16); s += __shfl_xor(s, 32);
;         if (fq == 0) unsafeAtomicAdd(ss + row, s);
;         if (m & 1) EPI_FENCE(); }
;   }
	v_pk_add_f32 v[60:61], v[60:61], v[170:171]
	v_pk_add_f32 v[62:63], v[62:63], v[172:173]
	v_pk_add_f32 v[56:57], v[56:57], v[174:175]
	v_pk_add_f32 v[58:59], v[58:59], v[176:177]
	v_pk_add_f32 v[52:53], v[52:53], v[178:179]
	v_pk_add_f32 v[54:55], v[54:55], v[180:181]
	v_pk_add_f32 v[48:49], v[48:49], v[182:183]
	v_pk_add_f32 v[50:51], v[50:51], v[184:185]
	v_add_u32_e32 v251, 0x100000, v148
	global_store_dwordx4 v251, v[60:63], s[72:73]
	global_store_dwordx4 v251, v[56:59], s[72:73] offset:16
	global_store_dwordx4 v251, v[52:55], s[72:73] offset:512
	global_store_dwordx4 v251, v[48:51], s[72:73] offset:528
	v_mul_f32_e32 v248, v60, v60
	v_mul_f32_e32 v249, v61, v61
	v_fmac_f32_e32 v248, v62, v62
	v_fmac_f32_e32 v249, v63, v63
	v_fmac_f32_e32 v248, v56, v56
	v_fmac_f32_e32 v249, v57, v57
	v_fmac_f32_e32 v248, v58, v58
	v_fmac_f32_e32 v249, v59, v59
	v_fmac_f32_e32 v248, v52, v52
	v_fmac_f32_e32 v249, v53, v53
	v_fmac_f32_e32 v248, v54, v54
	v_fmac_f32_e32 v249, v55, v55
	v_fmac_f32_e32 v248, v48, v48
	v_fmac_f32_e32 v249, v49, v49
	v_fmac_f32_e32 v248, v50, v50
	v_fmac_f32_e32 v249, v51, v51
	v_add_f32_e32 v248, v248, v249
	ds_bpermute_b32 v249, v186, v248
	v_pk_mul_f32 v[170:171], v[60:61], v[144:145]
	v_pk_mul_f32 v[172:173], v[62:63], v[146:147]
	v_pk_mul_f32 v[174:175], v[56:57], v[158:159]
	v_pk_mul_f32 v[176:177], v[58:59], v[160:161]
	v_pk_mul_f32 v[178:179], v[52:53], v[162:163]
	v_pk_mul_f32 v[180:181], v[54:55], v[164:165]
	v_pk_mul_f32 v[182:183], v[48:49], v[166:167]
	v_pk_mul_f32 v[184:185], v[50:51], v[168:169]
	v_cvt_pk_bf16_f32 v170, v170, v171
	v_cvt_pk_bf16_f32 v171, v172, v173
	v_cvt_pk_bf16_f32 v172, v174, v175
	v_cvt_pk_bf16_f32 v173, v176, v177
	v_cvt_pk_bf16_f32 v178, v178, v179
	v_cvt_pk_bf16_f32 v179, v180, v181
	v_cvt_pk_bf16_f32 v180, v182, v183
	v_cvt_pk_bf16_f32 v181, v184, v185
	v_lshrrev_b32_e32 v250, 1, v251
	global_store_dwordx4 v250, v[170:173], s[16:17]
	global_store_dwordx4 v250, v[178:181], s[16:17] offset:256
	s_waitcnt lgkmcnt(0)
	v_add_f32_e32 v248, v248, v249
	ds_bpermute_b32 v249, v252, v248
	v_add_u32_e32 v250, 0x200, v149
	s_waitcnt lgkmcnt(0)
	v_add_f32_e32 v248, v248, v249
	s_and_saveexec_b64 s[24:25], s[2:3]
	global_atomic_add_f32 v250, v248, s[18:19]
	s_mov_b64 exec, s[24:25]
	s_waitcnt vmcnt(30)
	v_pk_add_f32 v[44:45], v[44:45], v[188:189]
	v_pk_add_f32 v[46:47], v[46:47], v[190:191]
	v_pk_add_f32 v[40:41], v[40:41], v[194:195]
	v_pk_add_f32 v[42:43], v[42:43], v[196:197]
	v_pk_add_f32 v[36:37], v[36:37], v[198:199]
	v_pk_add_f32 v[38:39], v[38:39], v[200:201]
	v_pk_add_f32 v[32:33], v[32:33], v[202:203]
	v_pk_add_f32 v[34:35], v[34:35], v[204:205]
	v_add_u32_e32 v251, 0x120000, v148
	global_store_dwordx4 v251, v[44:47], s[72:73]
	global_store_dwordx4 v251, v[40:43], s[72:73] offset:16
	global_store_dwordx4 v251, v[36:39], s[72:73] offset:512
	global_store_dwordx4 v251, v[32:35], s[72:73] offset:528
	v_mul_f32_e32 v248, v44, v44
	v_mul_f32_e32 v249, v45, v45
	v_fmac_f32_e32 v248, v46, v46
	v_fmac_f32_e32 v249, v47, v47
	v_fmac_f32_e32 v248, v40, v40
	v_fmac_f32_e32 v249, v41, v41
	v_fmac_f32_e32 v248, v42, v42
	v_fmac_f32_e32 v249, v43, v43
	v_fmac_f32_e32 v248, v36, v36
	v_fmac_f32_e32 v249, v37, v37
	v_fmac_f32_e32 v248, v38, v38
	v_fmac_f32_e32 v249, v39, v39
	v_fmac_f32_e32 v248, v32, v32
	v_fmac_f32_e32 v249, v33, v33
	v_fmac_f32_e32 v248, v34, v34
	v_fmac_f32_e32 v249, v35, v35
	v_add_f32_e32 v248, v248, v249
	ds_bpermute_b32 v249, v186, v248
	v_pk_mul_f32 v[188:189], v[44:45], v[144:145]
	v_pk_mul_f32 v[190:191], v[46:47], v[146:147]
	v_pk_mul_f32 v[194:195], v[40:41], v[158:159]
	v_pk_mul_f32 v[196:197], v[42:43], v[160:161]
	v_pk_mul_f32 v[198:199], v[36:37], v[162:163]
	v_pk_mul_f32 v[200:201], v[38:39], v[164:165]
	v_pk_mul_f32 v[202:203], v[32:33], v[166:167]
	v_pk_mul_f32 v[204:205], v[34:35], v[168:169]
	v_cvt_pk_bf16_f32 v188, v188, v189
	v_cvt_pk_bf16_f32 v189, v190, v191
	v_cvt_pk_bf16_f32 v190, v194, v195
	v_cvt_pk_bf16_f32 v191, v196, v197
	v_cvt_pk_bf16_f32 v198, v198, v199
	v_cvt_pk_bf16_f32 v199, v200, v201
	v_cvt_pk_bf16_f32 v200, v202, v203
	v_cvt_pk_bf16_f32 v201, v204, v205
	v_lshrrev_b32_e32 v250, 1, v251
	global_store_dwordx4 v250, v[188:191], s[16:17]
	global_store_dwordx4 v250, v[198:201], s[16:17] offset:256
	s_waitcnt lgkmcnt(0)
	v_add_f32_e32 v248, v248, v249
	ds_bpermute_b32 v249, v252, v248
	v_add_u32_e32 v250, 0x240, v149
	s_waitcnt lgkmcnt(0)
	v_add_f32_e32 v248, v248, v249
	s_and_saveexec_b64 s[24:25], s[2:3]
	global_atomic_add_f32 v250, v248, s[18:19]
	s_mov_b64 exec, s[24:25]
	s_waitcnt vmcnt(26)
; #define EPI_FENCE() asm volatile("" ::: "memory")
; __device__ __forceinline__ u32x4 pack8(f32x4 a, f32x4 b) { u32x4 w; w.x = cvt_pk_bf16(a[0], a[1]); w.y = cvt_pk_bf16(a[2], a[3]); w.z = cvt_pk_bf16(b[0], b[1]); w.w = cvt_pk_bf16(b[2], b[3]); return w; }
; __device__ __forceinline__ float dot4(f32x4 a) { return (a[0] * a[0] + a[1] * a[1]) + (a[2] * a[2] + a[3] * a[3]); }
;   __device__ __forceinline__ void operator()(const AccT& acc, const pg8::Unit& u, int wr, int wc, int fr, int fq) const {
;     const int row0 = u.pm * 256 + wr * 64 + fr, col0 = u.pn * 256 + wc * 32 + 8 * fq;
; #pragma unroll
;     for (int ai = 0; ai < 2; ++ai)
; #pragma unroll
;       for (int m = 0; m < 4; ++m) { const int row = row0 + ai * 128 + m * 16; const size_t off = (size_t)row * DM + col0; float s = 0.f;
; #pragma unroll
;         for (int bj = 0; bj < 2; ++bj) { const int co = bj * 128;
;           const f32x4 v0 = *(const f32x4*)(base + off + co) + acc[ai][bj][m][0], v1 = *(const f32x4*)(base + off + co + 4) + acc[ai][bj][m][1];
;           *(f32x4*)(X + off + co) = v0; *(f32x4*)(X + off + co + 4) = v1; s += dot4(v0) + dot4(v1);
;           if (xb) { const f32x4 g0 = *(const f32x4*)(g + col0 + co), g1 = *(const f32x4*)(g + col0 + co + 4); *(u32x4*)(xb + off + co) = pack8(v0 * g0, v1 * g1); } }
;         s += __shfl_xor(s, 16); s += __shfl_xor(s, 32);
;         if (fq == 0) unsafeAtomicAdd(ss + row, s);
;         if (m & 1) EPI_FENCE(); }
;   }
	v_pk_add_f32 v[28:29], v[28:29], v[206:207]
	v_pk_add_f32 v[30:31], v[30:31], v[208:209]
	v_pk_add_f32 v[24:25], v[24:25], v[210:211]
	v_pk_add_f32 v[26:27], v[26:27], v[212:213]
	v_pk_add_f32 v[20:21], v[20:21], v[214:215]
	v_pk_add_f32 v[22:23], v[22:23], v[216:217]
	v_pk_add_f32 v[16:17], v[16:17], v[218:219]
	v_pk_add_f32 v[18:19], v[18:19], v[220:221]
	v_add_u32_e32 v251, 0x140000, v148
	global_store_dwordx4 v251, v[28:31], s[72:73]
	global_store_dwordx4 v251, v[24:27], s[72:73] offset:16
	global_store_dwordx4 v251, v[20:23], s[72:73] offset:512
	global_store_dwordx4 v251, v[16:19], s[72:73] offset:528
	v_mul_f32_e32 v248, v28, v28
	v_mul_f32_e32 v249, v29, v29
	v_fmac_f32_e32 v248, v30, v30
	v_fmac_f32_e32 v249, v31, v31
	v_fmac_f32_e32 v248, v24, v24
	v_fmac_f32_e32 v249, v25, v25
	v_fmac_f32_e32 v248, v26, v26
	v_fmac_f32_e32 v249, v27, v27
	v_fmac_f32_e32 v248, v20, v20
	v_fmac_f32_e32 v249, v21, v21
	v_fmac_f32_e32 v248, v22, v22
	v_fmac_f32_e32 v249, v23, v23
	v_fmac_f32_e32 v248, v16, v16
	v_fmac_f32_e32 v249, v17, v17
	v_fmac_f32_e32 v248, v18, v18
	v_fmac_f32_e32 v249, v19, v19
	v_add_f32_e32 v248, v248, v249
	ds_bpermute_b32 v249, v186, v248
	v_pk_mul_f32 v[206:207], v[28:29], v[144:145]
	v_pk_mul_f32 v[208:209], v[30:31], v[146:147]
	v_pk_mul_f32 v[210:211], v[24:25], v[158:159]
	v_pk_mul_f32 v[212:213], v[26:27], v[160:161]
	v_pk_mul_f32 v[214:215], v[20:21], v[162:163]
	v_pk_mul_f32 v[216:217], v[22:23], v[164:165]
	v_pk_mul_f32 v[218:219], v[16:17], v[166:167]
	v_pk_mul_f32 v[220:221], v[18:19], v[168:169]
	v_cvt_pk_bf16_f32 v206, v206, v207
	v_cvt_pk_bf16_f32 v207, v208, v209
	v_cvt_pk_bf16_f32 v208, v210, v211
	v_cvt_pk_bf16_f32 v209, v212, v213
	v_cvt_pk_bf16_f32 v214, v214, v215
	v_cvt_pk_bf16_f32 v215, v216, v217
	v_cvt_pk_bf16_f32 v216, v218, v219
	v_cvt_pk_bf16_f32 v217, v220, v221
	v_lshrrev_b32_e32 v250, 1, v251
	global_store_dwordx4 v250, v[206:209], s[16:17]
	global_store_dwordx4 v250, v[214:217], s[16:17] offset:256
	s_waitcnt lgkmcnt(0)
	v_add_f32_e32 v248, v248, v249
	ds_bpermute_b32 v249, v252, v248
	v_add_u32_e32 v250, 0x280, v149
	s_waitcnt lgkmcnt(0)
	v_add_f32_e32 v248, v248, v249
	s_and_saveexec_b64 s[24:25], s[2:3]
	global_atomic_add_f32 v250, v248, s[18:19]
	s_mov_b64 exec, s[24:25]
	s_waitcnt vmcnt(22)
	v_pk_add_f32 v[12:13], v[12:13], v[232:233]
	v_pk_add_f32 v[14:15], v[14:15], v[234:235]
	v_pk_add_f32 v[8:9], v[8:9], v[236:237]
	v_pk_add_f32 v[10:11], v[10:11], v[238:239]
	v_pk_add_f32 v[4:5], v[4:5], v[240:241]
	v_pk_add_f32 v[6:7], v[6:7], v[242:243]
	v_pk_add_f32 v[0:1], v[0:1], v[244:245]
	v_pk_add_f32 v[2:3], v[2:3], v[246:247]
	v_add_u32_e32 v251, 0x160000, v148
	global_store_dwordx4 v251, v[12:15], s[72:73]
	global_store_dwordx4 v251, v[8:11], s[72:73] offset:16
	global_store_dwordx4 v251, v[4:7], s[72:73] offset:512
	global_store_dwordx4 v251, v[0:3], s[72:73] offset:528
	v_mul_f32_e32 v248, v12, v12
	v_mul_f32_e32 v249, v13, v13
	v_fmac_f32_e32 v248, v14, v14
	v_fmac_f32_e32 v249, v15, v15
	v_fmac_f32_e32 v248, v8, v8
	v_fmac_f32_e32 v249, v9, v9
	v_fmac_f32_e32 v248, v10, v10
	v_fmac_f32_e32 v249, v11, v11
	v_fmac_f32_e32 v248, v4, v4
	v_fmac_f32_e32 v249, v5, v5
	v_fmac_f32_e32 v248, v6, v6
	v_fmac_f32_e32 v249, v7, v7
	v_fmac_f32_e32 v248, v0, v0
	v_fmac_f32_e32 v249, v1, v1
	v_fmac_f32_e32 v248, v2, v2
	v_fmac_f32_e32 v249, v3, v3
	v_add_f32_e32 v248, v248, v249
	ds_bpermute_b32 v249, v186, v248
	v_pk_mul_f32 v[232:233], v[12:13], v[144:145]
	v_pk_mul_f32 v[234:235], v[14:15], v[146:147]
	v_pk_mul_f32 v[236:237], v[8:9], v[158:159]
	v_pk_mul_f32 v[238:239], v[10:11], v[160:161]
	v_pk_mul_f32 v[240:241], v[4:5], v[162:163]
	v_pk_mul_f32 v[242:243], v[6:7], v[164:165]
	v_pk_mul_f32 v[244:245], v[0:1], v[166:167]
	v_pk_mul_f32 v[246:247], v[2:3], v[168:169]
	v_cvt_pk_bf16_f32 v232, v232, v233
	v_cvt_pk_bf16_f32 v233, v234, v235
	v_cvt_pk_bf16_f32 v234, v236, v237
	v_cvt_pk_bf16_f32 v235, v238, v239
	v_cvt_pk_bf16_f32 v240, v240, v241
	v_cvt_pk_bf16_f32 v241, v242, v243
	v_cvt_pk_bf16_f32 v242, v244, v245
	v_cvt_pk_bf16_f32 v243, v246, v247
	v_lshrrev_b32_e32 v250, 1, v251
	global_store_dwordx4 v250, v[232:235], s[16:17]
	global_store_dwordx4 v250, v[240:243], s[16:17] offset:256
	s_waitcnt lgkmcnt(0)
	v_add_f32_e32 v248, v248, v249
	ds_bpermute_b32 v249, v252, v248
	v_add_u32_e32 v250, 0x2c0, v149
	s_waitcnt lgkmcnt(0)
	v_add_f32_e32 v248, v248, v249
	s_and_saveexec_b64 s[24:25], s[2:3]
	global_atomic_add_f32 v250, v248, s[18:19]
	s_mov_b64 exec, s[24:25]
	s_branch .LBB0_775
